# attn0: P-fragment permlane swaps removed (56 sites) by staging the V tile with natural key order (LDS-DMA source rows no longer swap key bits 2/3)
# speedup vs baseline: 1.0340x; 1.0052x over previous
.LBB0_303:
	v_mbcnt_lo_u32_b32 v195, -1, 0
	v_mbcnt_hi_u32_b32 v195, -1, v195
	s_movk_i32 s6, 0x400
	v_bfe_u32 v3, v195, 4, 2
	v_and_b32_e32 v5, 15, v195
	s_waitcnt lgkmcnt(1)
	v_or_b32_e32 v4, s85, v3
	v_bitop3_b32 v6, v3, v195, 15 bitop3:0x78
	v_bitop3_b32 v3, v3, v5, 4 bitop3:0x36
	v_lshlrev_b32_e32 v4, 8, v4
	v_lshlrev_b32_e32 v3, 4, v3
	v_lshl_or_b32 v197, v6, 4, v4
	v_or3_b32 v198, v3, v4, s6
	v_bfe_u32 v3, v195, 2, 3
	v_lshrrev_b32_e32 v4, 2, v195
	v_and_b32_e32 v196, 63, v195
	v_bitop3_b32 v3, v3, 51, s85 bitop3:0xc8
	v_and_b32_e32 v4, 4, v4
	s_waitcnt lgkmcnt(0)
	v_lshlrev_b32_e32 v1, 3, v196
	v_lshl_or_b32 v3, s96, 1, v3
	v_or_b32_e32 v3, v4, v3
	v_and_b32_e32 v2, 24, v1
	v_lshlrev_b32_e32 v3, 7, v3
	v_and_b32_e32 v4, 32, v195
	v_or3_b32 v3, v3, v4, v2
	v_lshlrev_b32_e32 v199, 1, v3
	s_andn2_b64 vcc, exec, s[56:57]
	v_or_b32_e32 v200, 0x80, v199
	s_cbranch_vccnz .LBB0_305
	s_mov_b32 s6, m0
	s_mov_b32 m0, s42
	s_nop 0
	global_load_lds_dwordx4 v197, s[4:5]
	s_mov_b32 m0, s6
	s_add_u32 s44, s4, 0x4000
	s_mov_b32 s6, m0
	s_mov_b32 m0, s43
	s_nop 0
	global_load_lds_dwordx4 v198, s[4:5]
	s_mov_b32 m0, s6
	s_addc_u32 s45, s5, 0
	s_mov_b32 s6, m0
	s_mov_b32 m0, s97
	s_nop 0
	global_load_lds_dwordx4 v199, s[58:59]
	s_mov_b32 m0, s6
	v_readlane_b32 s21, v255, 31
	s_mov_b32 s6, m0
	s_mov_b32 m0, s91
	s_nop 0
	global_load_lds_dwordx4 v200, s[58:59]
	s_mov_b32 m0, s6
	s_mov_b32 s69, 0x8000
	s_mov_b32 s6, m0
	s_mov_b32 m0, s21
	s_nop 0
	global_load_lds_dwordx4 v197, s[44:45]
	s_mov_b32 m0, s6
	s_mov_b32 s72, 0
	s_mov_b32 s6, m0
	s_mov_b32 m0, s95
	s_nop 0
	global_load_lds_dwordx4 v198, s[44:45]
	s_mov_b32 m0, s6
	s_movk_i32 s74, 0x4000

.LBB0_309:
	s_mov_b32 s77, s74
	v_add3_u32 v215, s77, v209, v208
	v_add3_u32 v216, s77, v210, v208
	v_add3_u32 v233, s77, v211, v208
	v_add3_u32 v254, s77, v212, v208
	ds_read_b128 v[234:237], v215 offset:49152
	ds_read_b128 v[238:241], v215 offset:57344
	ds_read_b128 v[242:245], v216 offset:49152
	ds_read_b128 v[246:249], v216 offset:57344
	ds_read_b128 v[250:253], v233 offset:49152
	s_add_u32 s4, s70, 0xffffc000
	s_mov_b32 s74, s72
	s_addc_u32 s5, s71, -1
	s_add_i32 s72, s72, s42
	s_setprio 1
	s_waitcnt lgkmcnt(4)
	v_mfma_f32_32x32x16_bf16 v[112:127], v[234:237], v[188:191], 0
	ds_read_b128 v[234:237], v233 offset:57344
	v_add_f32_e32 v1, 0, v230
	v_add_f32_e32 v1, v232, v1
	v_add_f32_e32 v1, v228, v1
	v_add_f32_e32 v1, v231, v1
	v_add_f32_e32 v1, v226, v1
	s_waitcnt lgkmcnt(4)
	v_mfma_f32_32x32x16_bf16 v[96:111], v[238:241], v[188:191], 0
	ds_read_b128 v[238:241], v254 offset:49152
	v_add_f32_e32 v1, v229, v1
	v_add_f32_e32 v1, v225, v1
	v_add_f32_e32 v1, v227, v1
	v_add_f32_e32 v1, v222, v1
	v_add_f32_e32 v1, v224, v1
	s_waitcnt lgkmcnt(4)
	v_mfma_f32_32x32x16_bf16 v[112:127], v[242:245], v[184:187], v[112:127]
	ds_read_b128 v[242:245], v254 offset:57344
	s_mov_b32 s73, m0
	s_mov_b32 m0, s72
	s_nop 0
	global_load_lds_dwordx4 v197, s[4:5]
	s_mov_b32 m0, s73
	v_add_f32_e32 v1, v220, v1
	v_add_f32_e32 v1, v223, v1
	v_exp_f32_e32 v2, v128
	v_add_f32_e32 v1, v218, v1
	s_waitcnt lgkmcnt(4)
	v_mfma_f32_32x32x16_bf16 v[96:111], v[246:249], v[184:187], v[96:111]
	ds_read_b128 v[246:249], v215 offset:49280
	v_exp_f32_e32 v12, v129
	v_add_f32_e32 v1, v221, v1
	v_exp_f32_e32 v13, v130
	v_add_f32_e32 v1, v217, v1
	s_waitcnt lgkmcnt(4)
	v_mfma_f32_32x32x16_bf16 v[112:127], v[250:253], v[180:183], v[112:127]
	ds_read_b128 v[250:253], v215 offset:57472
	v_exp_f32_e32 v14, v131
	v_add_f32_e32 v1, v219, v1
	v_exp_f32_e32 v15, v132
	s_waitcnt lgkmcnt(4)
	v_mfma_f32_32x32x16_bf16 v[96:111], v[234:237], v[180:183], v[96:111]
	ds_read_b128 v[234:237], v216 offset:49280
	s_addk_i32 s72, 0x400
	s_mov_b32 s73, m0
	s_mov_b32 m0, s72
	s_nop 0
	global_load_lds_dwordx4 v198, s[4:5]
	s_mov_b32 m0, s73
	v_add_f32_e32 v1, v2, v1
	v_exp_f32_e32 v18, v133
	v_add_f32_e32 v1, v12, v1
	s_waitcnt lgkmcnt(4)
	v_mfma_f32_32x32x16_bf16 v[112:127], v[238:241], v[176:179], v[112:127]
	ds_read_b128 v[238:241], v216 offset:57472
	v_exp_f32_e32 v19, v134
	v_add_f32_e32 v1, v13, v1
	v_exp_f32_e32 v20, v135
	v_add_f32_e32 v1, v14, v1
	s_waitcnt lgkmcnt(4)
	v_mfma_f32_32x32x16_bf16 v[96:111], v[242:245], v[176:179], v[96:111]
	ds_read_b128 v[242:245], v233 offset:49280
	v_exp_f32_e32 v21, v136
	v_add_f32_e32 v1, v15, v1
	v_exp_f32_e32 v22, v137
	s_waitcnt lgkmcnt(4)
	v_mfma_f32_32x32x16_bf16 v[112:127], v[246:249], v[172:175], v[112:127]
	ds_read_b128 v[246:249], v233 offset:57472
	s_add_i32 s4, s69, s97
	s_mov_b32 s5, m0
	s_mov_b32 m0, s4
	s_nop 0
	global_load_lds_dwordx4 v199, s[56:57]
	s_mov_b32 m0, s5
	v_add_f32_e32 v1, v18, v1
	v_exp_f32_e32 v23, v138
	v_add_f32_e32 v1, v19, v1
	v_exp_f32_e32 v24, v139
	s_waitcnt lgkmcnt(4)
	v_mfma_f32_32x32x16_bf16 v[96:111], v[250:253], v[172:175], v[96:111]
	ds_read_b128 v[250:253], v254 offset:49280
	v_add_f32_e32 v1, v20, v1
	v_exp_f32_e32 v25, v140
	v_add_f32_e32 v1, v21, v1
	s_waitcnt lgkmcnt(4)
	v_mfma_f32_32x32x16_bf16 v[112:127], v[234:237], v[168:171], v[112:127]
	ds_read_b128 v[234:237], v254 offset:57472
	v_exp_f32_e32 v26, v141
	v_add_f32_e32 v1, v22, v1
	v_exp_f32_e32 v27, v142
	v_add_f32_e32 v1, v23, v1
	s_waitcnt lgkmcnt(4)
	v_mfma_f32_32x32x16_bf16 v[96:111], v[238:241], v[168:171], v[96:111]
	s_addk_i32 s4, 0x400
	s_mov_b32 s5, m0
	s_mov_b32 m0, s4
	s_nop 0
	global_load_lds_dwordx4 v200, s[56:57]
	s_mov_b32 m0, s5
	v_exp_f32_e32 v28, v143
	v_add_f32_e32 v1, v24, v1
	v_add_f32_e32 v1, v25, v1
	v_add_f32_e32 v1, v26, v1
	s_waitcnt lgkmcnt(3)
	v_mfma_f32_32x32x16_bf16 v[112:127], v[242:245], v[164:167], v[112:127]
	v_add_f32_e32 v1, v27, v1
	v_add_f32_e32 v1, v28, v1
	v_mov_b32_e32 v3, v1
	v_cvt_pk_bf16_f32 v4, v230, v232
	v_cvt_pk_bf16_f32 v5, v228, v231
	s_waitcnt lgkmcnt(2)
	v_mfma_f32_32x32x16_bf16 v[96:111], v[246:249], v[164:167], v[96:111]
	v_cvt_pk_bf16_f32 v6, v226, v229
	s_nop 1
	v_permlane32_swap_b32_e32 v1, v3
	v_cvt_pk_bf16_f32 v7, v225, v227
	v_cvt_pk_bf16_f32 v8, v222, v224
	v_cvt_pk_bf16_f32 v9, v220, v223
	s_waitcnt lgkmcnt(1)
	v_mfma_f32_32x32x16_bf16 v[112:127], v[250:253], v[160:163], v[112:127]
	v_cvt_pk_bf16_f32 v10, v218, v221
	v_cvt_pk_bf16_f32 v11, v217, v219
	v_cvt_pk_bf16_f32 v12, v2, v12
	v_cvt_pk_bf16_f32 v13, v13, v14
	v_cvt_pk_bf16_f32 v14, v15, v18
	s_waitcnt lgkmcnt(0)
	v_mfma_f32_32x32x16_bf16 v[96:111], v[234:237], v[160:163], v[96:111]
	v_cvt_pk_bf16_f32 v15, v19, v20
	v_cvt_pk_bf16_f32 v18, v21, v22
	v_cvt_pk_bf16_f32 v19, v23, v24
	v_cvt_pk_bf16_f32 v20, v25, v26
	v_cvt_pk_bf16_f32 v21, v27, v28
	s_setprio 0
	v_add_u32_e32 v2, s74, v206
	ds_read_b64_tr_b16 v[22:23], v2 offset:0
	ds_read_b64_tr_b16 v[24:25], v2 offset:0x800
	ds_read_b64_tr_b16 v[26:27], v2 offset:0x1000
	ds_read_b64_tr_b16 v[28:29], v2 offset:0x1800
	ds_read_b64_tr_b16 v[128:129], v2 offset:0x2000
	ds_read_b64_tr_b16 v[130:131], v2 offset:0x2800
	ds_read_b64_tr_b16 v[132:133], v2 offset:0x3000
	ds_read_b64_tr_b16 v[134:135], v2 offset:0x3800
	s_waitcnt lgkmcnt(6)
	s_nop 0
	v_mfma_f32_32x32x16_bf16 v[32:47], v[4:7], v[22:25], v[32:47]
	ds_read_b64_tr_b16 v[22:23], v2 offset:0x200
	ds_read_b64_tr_b16 v[24:25], v2 offset:0xa00
	s_waitcnt lgkmcnt(6)
	v_mfma_f32_32x32x16_bf16 v[32:47], v[8:11], v[26:29], v[32:47]
	ds_read_b64_tr_b16 v[26:27], v2 offset:0x1200
	ds_read_b64_tr_b16 v[28:29], v2 offset:0x1a00
	s_waitcnt lgkmcnt(6)
	v_mfma_f32_32x32x16_bf16 v[32:47], v[12:15], v[128:131], v[32:47]
	ds_read_b64_tr_b16 v[128:129], v2 offset:0x2200
	ds_read_b64_tr_b16 v[130:131], v2 offset:0x2a00
	s_waitcnt lgkmcnt(6)
	v_mfma_f32_32x32x16_bf16 v[32:47], v[18:21], v[132:135], v[32:47]
	ds_read_b64_tr_b16 v[132:133], v2 offset:0x3200
	ds_read_b64_tr_b16 v[134:135], v2 offset:0x3a00
	s_waitcnt lgkmcnt(6)
	v_mfma_f32_32x32x16_bf16 v[48:63], v[4:7], v[22:25], v[48:63]
	ds_read_b64_tr_b16 v[22:23], v2 offset:0x400
	ds_read_b64_tr_b16 v[24:25], v2 offset:0xc00
	s_waitcnt lgkmcnt(6)
	v_mfma_f32_32x32x16_bf16 v[48:63], v[8:11], v[26:29], v[48:63]
	ds_read_b64_tr_b16 v[26:27], v2 offset:0x1400
	ds_read_b64_tr_b16 v[28:29], v2 offset:0x1c00
	s_waitcnt lgkmcnt(6)
	v_mfma_f32_32x32x16_bf16 v[48:63], v[12:15], v[128:131], v[48:63]
	ds_read_b64_tr_b16 v[128:129], v2 offset:0x2400
	ds_read_b64_tr_b16 v[130:131], v2 offset:0x2c00
	s_waitcnt lgkmcnt(6)
	v_mfma_f32_32x32x16_bf16 v[48:63], v[18:21], v[132:135], v[48:63]
	ds_read_b64_tr_b16 v[132:133], v2 offset:0x3400
	ds_read_b64_tr_b16 v[134:135], v2 offset:0x3c00
	s_waitcnt lgkmcnt(6)
	v_mfma_f32_32x32x16_bf16 v[64:79], v[4:7], v[22:25], v[64:79]
	ds_read_b64_tr_b16 v[22:23], v2 offset:0x600
	ds_read_b64_tr_b16 v[24:25], v2 offset:0xe00
	s_waitcnt lgkmcnt(6)
	v_mfma_f32_32x32x16_bf16 v[64:79], v[8:11], v[26:29], v[64:79]
	ds_read_b64_tr_b16 v[26:27], v2 offset:0x1600
	ds_read_b64_tr_b16 v[28:29], v2 offset:0x1e00
	s_waitcnt lgkmcnt(6)
	v_mfma_f32_32x32x16_bf16 v[64:79], v[12:15], v[128:131], v[64:79]
	ds_read_b64_tr_b16 v[128:129], v2 offset:0x2600
	ds_read_b64_tr_b16 v[130:131], v2 offset:0x2e00
	s_waitcnt lgkmcnt(6)
	v_mfma_f32_32x32x16_bf16 v[64:79], v[18:21], v[132:135], v[64:79]
	ds_read_b64_tr_b16 v[132:133], v2 offset:0x3600
	ds_read_b64_tr_b16 v[134:135], v2 offset:0x3e00
	s_waitcnt lgkmcnt(6)
	v_mfma_f32_32x32x16_bf16 v[80:95], v[4:7], v[22:25], v[80:95]
	v_max_f32_e32 v2, v113, v112
	v_max3_f32 v2, v2, v114, v115
	v_max3_f32 v2, v2, v116, v117
	v_max3_f32 v2, v2, v118, v119
	v_max3_f32 v2, v2, v120, v121
	v_max3_f32 v2, v2, v122, v123
	v_max3_f32 v2, v2, v124, v125
	v_max3_f32 v2, v2, v126, v127
	s_waitcnt lgkmcnt(4)
	v_mfma_f32_32x32x16_bf16 v[80:95], v[8:11], v[26:29], v[80:95]
	v_max3_f32 v2, v2, v96, v97
	v_max3_f32 v2, v2, v98, v99
	v_max3_f32 v2, v2, v100, v101
	v_max3_f32 v2, v2, v102, v103
	v_max3_f32 v2, v2, v104, v105
	v_max3_f32 v2, v2, v106, v107
	v_max3_f32 v2, v2, v108, v109
	v_max3_f32 v2, v2, v110, v111
	s_waitcnt lgkmcnt(2)
	v_mfma_f32_32x32x16_bf16 v[80:95], v[12:15], v[128:131], v[80:95]
	v_mov_b32_e32 v4, v2
	s_nop 1
	v_permlane32_swap_b32_e32 v2, v4
	v_max_f32_e32 v2, v4, v2
	v_sub_f32_e32 v4, v2, v214
	v_cmp_ge_f32_e32 vcc, 0x42b504f3, v4
	v_max_f32_e32 v2, v214, v2
	s_waitcnt lgkmcnt(0)
	v_mfma_f32_32x32x16_bf16 v[80:95], v[18:21], v[132:135], v[80:95]
	s_cmp_eq_u64 vcc, exec
	s_cbranch_scc0 .Lattn0_slowA
	v_mov_b32_e32 v4, 1.0
	v_mov_b32_e32 v2, v214
.Lattn0_backA:
	s_waitcnt vmcnt(4) lgkmcnt(0)
	s_barrier
	v_add3_u32 v215, s69, v209, v208
	v_add3_u32 v216, s69, v210, v208
	v_add3_u32 v233, s69, v211, v208
	v_add3_u32 v254, s69, v212, v208
	ds_read_b128 v[234:237], v215 offset:49152
	ds_read_b128 v[238:241], v215 offset:57344
	ds_read_b128 v[242:245], v216 offset:49152
	ds_read_b128 v[246:249], v216 offset:57344
	ds_read_b128 v[250:253], v233 offset:49152
	v_mul_f32_e32 v5, 0xbe0293ee, v2
	v_fmamk_f32 v6, v112, 0x3e0293ee, v5
	v_fmamk_f32 v7, v113, 0x3e0293ee, v5
	v_fmamk_f32 v8, v114, 0x3e0293ee, v5
	v_fmamk_f32 v9, v115, 0x3e0293ee, v5
	v_fmamk_f32 v10, v116, 0x3e0293ee, v5
	v_fmamk_f32 v11, v117, 0x3e0293ee, v5
	v_fmamk_f32 v12, v118, 0x3e0293ee, v5
	v_fmamk_f32 v13, v119, 0x3e0293ee, v5
	v_fmamk_f32 v14, v120, 0x3e0293ee, v5
	v_fmamk_f32 v15, v121, 0x3e0293ee, v5
	v_fmamk_f32 v18, v122, 0x3e0293ee, v5
	v_fmamk_f32 v19, v123, 0x3e0293ee, v5
	v_fmamk_f32 v20, v124, 0x3e0293ee, v5
	v_fmamk_f32 v21, v125, 0x3e0293ee, v5
	v_fmamk_f32 v22, v126, 0x3e0293ee, v5
	v_fmamk_f32 v23, v127, 0x3e0293ee, v5
	v_fmamk_f32 v24, v96, 0x3e0293ee, v5
	v_fmamk_f32 v25, v97, 0x3e0293ee, v5
	v_fmamk_f32 v26, v98, 0x3e0293ee, v5
	v_fmamk_f32 v27, v99, 0x3e0293ee, v5
	v_fmamk_f32 v28, v100, 0x3e0293ee, v5
	v_fmamk_f32 v29, v101, 0x3e0293ee, v5
	v_fmamk_f32 v30, v102, 0x3e0293ee, v5
	v_fmamk_f32 v31, v103, 0x3e0293ee, v5
	v_fmamk_f32 v128, v104, 0x3e0293ee, v5
	v_fmamk_f32 v129, v105, 0x3e0293ee, v5
	v_fmamk_f32 v130, v106, 0x3e0293ee, v5
	v_fmamk_f32 v131, v107, 0x3e0293ee, v5
	v_fmamk_f32 v132, v108, 0x3e0293ee, v5
	v_fmamk_f32 v133, v109, 0x3e0293ee, v5
	v_fmamk_f32 v134, v110, 0x3e0293ee, v5
	v_fmac_f32_e32 v5, 0x3e0293ee, v111
	s_setprio 1
	s_waitcnt lgkmcnt(4)
	v_mfma_f32_32x32x16_bf16 v[112:127], v[234:237], v[188:191], 0
	ds_read_b128 v[234:237], v233 offset:57344
	v_exp_f32_e32 v135, v6
	v_exp_f32_e32 v136, v7
	v_exp_f32_e32 v137, v8
	v_exp_f32_e32 v138, v9
	s_waitcnt lgkmcnt(4)
	v_mfma_f32_32x32x16_bf16 v[96:111], v[238:241], v[188:191], 0
	ds_read_b128 v[238:241], v254 offset:49152
	v_exp_f32_e32 v10, v10
	v_exp_f32_e32 v11, v11
	v_exp_f32_e32 v12, v12
	s_waitcnt lgkmcnt(4)
	v_mfma_f32_32x32x16_bf16 v[112:127], v[242:245], v[184:187], v[112:127]
	ds_read_b128 v[242:245], v254 offset:57344
	s_add_i32 s4, s77, s42
	s_mov_b32 s5, m0
	s_mov_b32 m0, s4
	s_nop 0
	global_load_lds_dwordx4 v197, s[70:71]
	s_mov_b32 m0, s5
	v_exp_f32_e32 v13, v13
	v_exp_f32_e32 v14, v14
	v_exp_f32_e32 v15, v15
	v_exp_f32_e32 v18, v18
	s_waitcnt lgkmcnt(4)
	v_mfma_f32_32x32x16_bf16 v[96:111], v[246:249], v[184:187], v[96:111]
	ds_read_b128 v[246:249], v215 offset:49280
	v_exp_f32_e32 v19, v19
	v_exp_f32_e32 v20, v20
	v_exp_f32_e32 v21, v21
	s_waitcnt lgkmcnt(4)
	v_mfma_f32_32x32x16_bf16 v[112:127], v[250:253], v[180:183], v[112:127]
	ds_read_b128 v[250:253], v215 offset:57472
	v_exp_f32_e32 v22, v22
	v_exp_f32_e32 v23, v23
	v_exp_f32_e32 v7, v24
	v_exp_f32_e32 v24, v25
	s_waitcnt lgkmcnt(4)
	v_mfma_f32_32x32x16_bf16 v[96:111], v[234:237], v[180:183], v[96:111]
	ds_read_b128 v[234:237], v216 offset:49280
	s_addk_i32 s4, 0x400
	s_mov_b32 s5, m0
	s_mov_b32 m0, s4
	s_nop 0
	global_load_lds_dwordx4 v198, s[70:71]
	s_mov_b32 m0, s5
	v_exp_f32_e32 v25, v26
	v_exp_f32_e32 v26, v27
	v_exp_f32_e32 v27, v28
	s_waitcnt lgkmcnt(4)
	v_mfma_f32_32x32x16_bf16 v[112:127], v[238:241], v[176:179], v[112:127]
	ds_read_b128 v[238:241], v216 offset:57472
	v_exp_f32_e32 v28, v29
	v_exp_f32_e32 v29, v30
	v_exp_f32_e32 v30, v31
	v_exp_f32_e32 v31, v128
	s_waitcnt lgkmcnt(4)
	v_mfma_f32_32x32x16_bf16 v[96:111], v[242:245], v[176:179], v[96:111]
	ds_read_b128 v[242:245], v233 offset:49280
	v_exp_f32_e32 v128, v129
	v_exp_f32_e32 v129, v130
	v_exp_f32_e32 v130, v131
	v_exp_f32_e32 v131, v132
	s_waitcnt lgkmcnt(4)
	v_mfma_f32_32x32x16_bf16 v[112:127], v[246:249], v[172:175], v[112:127]
	ds_read_b128 v[246:249], v233 offset:57472
	s_add_u32 s4, s56, 0x4000
	s_addc_u32 s5, s57, 0
	s_add_i32 s72, s74, s97
	s_mov_b32 s73, m0
	s_mov_b32 m0, s72
	s_nop 0
	global_load_lds_dwordx4 v199, s[4:5]
	s_mov_b32 m0, s73
	v_exp_f32_e32 v132, v133
	v_exp_f32_e32 v133, v134
	v_exp_f32_e32 v134, v5
	s_waitcnt lgkmcnt(4)
	v_mfma_f32_32x32x16_bf16 v[96:111], v[250:253], v[172:175], v[96:111]
	ds_read_b128 v[250:253], v254 offset:49280
	v_add_f32_e32 v5, 0, v135
	v_add_f32_e32 v5, v136, v5
	v_add_f32_e32 v5, v137, v5
	v_add_f32_e32 v5, v138, v5
	v_add_f32_e32 v5, v10, v5
	v_add_f32_e32 v5, v11, v5
	v_add_f32_e32 v5, v12, v5
	v_add_f32_e32 v5, v13, v5
	s_waitcnt lgkmcnt(4)
	v_mfma_f32_32x32x16_bf16 v[112:127], v[234:237], v[168:171], v[112:127]
	ds_read_b128 v[234:237], v254 offset:57472
	v_add_f32_e32 v5, v14, v5
	v_add_f32_e32 v5, v15, v5
	v_add_f32_e32 v5, v18, v5
	v_add_f32_e32 v5, v19, v5
	v_add_f32_e32 v5, v20, v5
	v_add_f32_e32 v5, v21, v5
	v_add_f32_e32 v5, v22, v5
	s_waitcnt lgkmcnt(4)
	v_mfma_f32_32x32x16_bf16 v[96:111], v[238:241], v[168:171], v[96:111]
	s_addk_i32 s72, 0x400
	s_mov_b32 s73, m0
	s_mov_b32 m0, s72
	s_nop 0
	global_load_lds_dwordx4 v200, s[4:5]
	s_mov_b32 m0, s73
	v_add_f32_e32 v5, v23, v5
	v_add_f32_e32 v5, v7, v5
	v_add_f32_e32 v5, v24, v5
	v_add_f32_e32 v5, v25, v5
	v_add_f32_e32 v5, v26, v5
	v_add_f32_e32 v5, v27, v5
	v_add_f32_e32 v5, v28, v5
	s_waitcnt lgkmcnt(3)
	v_mfma_f32_32x32x16_bf16 v[112:127], v[242:245], v[164:167], v[112:127]
	v_add_f32_e32 v5, v29, v5
	v_add_f32_e32 v5, v30, v5
	v_add_f32_e32 v5, v31, v5
	v_add_f32_e32 v5, v128, v5
	v_add_f32_e32 v5, v129, v5
	v_add_f32_e32 v5, v130, v5
	v_add_f32_e32 v5, v131, v5
	s_waitcnt lgkmcnt(2)
	v_mfma_f32_32x32x16_bf16 v[96:111], v[246:249], v[164:167], v[96:111]
	v_add_f32_e32 v5, v132, v5
	v_add_f32_e32 v5, v133, v5
	v_add_f32_e32 v5, v134, v5
	v_mov_b32_e32 v6, v5
	v_cvt_pk_bf16_f32 v8, v135, v136
	v_cvt_pk_bf16_f32 v9, v137, v138
	v_cvt_pk_bf16_f32 v10, v10, v11
	s_waitcnt lgkmcnt(1)
	v_mfma_f32_32x32x16_bf16 v[112:127], v[250:253], v[160:163], v[112:127]
	s_nop 1
	v_permlane32_swap_b32_e32 v5, v6
	v_cvt_pk_bf16_f32 v11, v12, v13
	v_cvt_pk_bf16_f32 v12, v14, v15
	v_cvt_pk_bf16_f32 v13, v18, v19
	v_cvt_pk_bf16_f32 v14, v20, v21
	v_cvt_pk_bf16_f32 v15, v22, v23
	v_cvt_pk_bf16_f32 v18, v7, v24
	s_waitcnt lgkmcnt(0)
	v_mfma_f32_32x32x16_bf16 v[96:111], v[234:237], v[160:163], v[96:111]
	v_cvt_pk_bf16_f32 v19, v25, v26
	v_cvt_pk_bf16_f32 v20, v27, v28
	v_cvt_pk_bf16_f32 v21, v29, v30
	v_cvt_pk_bf16_f32 v22, v31, v128
	v_cvt_pk_bf16_f32 v23, v129, v130
	v_cvt_pk_bf16_f32 v24, v131, v132
	v_cvt_pk_bf16_f32 v25, v133, v134
	s_setprio 0
	v_add_u32_e32 v7, s77, v206
	ds_read_b64_tr_b16 v[26:27], v7 offset:0
	ds_read_b64_tr_b16 v[28:29], v7 offset:0x800
	ds_read_b64_tr_b16 v[128:129], v7 offset:0x1000
	ds_read_b64_tr_b16 v[130:131], v7 offset:0x1800
	ds_read_b64_tr_b16 v[132:133], v7 offset:0x2000
	ds_read_b64_tr_b16 v[134:135], v7 offset:0x2800
	ds_read_b64_tr_b16 v[136:137], v7 offset:0x3000
	ds_read_b64_tr_b16 v[138:139], v7 offset:0x3800
	s_waitcnt lgkmcnt(6)
	s_nop 0
	v_mfma_f32_32x32x16_bf16 v[32:47], v[8:11], v[26:29], v[32:47]
	ds_read_b64_tr_b16 v[26:27], v7 offset:0x200
	ds_read_b64_tr_b16 v[28:29], v7 offset:0xa00
	s_waitcnt lgkmcnt(6)
	v_mfma_f32_32x32x16_bf16 v[32:47], v[12:15], v[128:131], v[32:47]
	ds_read_b64_tr_b16 v[128:129], v7 offset:0x1200
	ds_read_b64_tr_b16 v[130:131], v7 offset:0x1a00
	s_waitcnt lgkmcnt(6)
	v_mfma_f32_32x32x16_bf16 v[32:47], v[18:21], v[132:135], v[32:47]
	ds_read_b64_tr_b16 v[132:133], v7 offset:0x2200
	ds_read_b64_tr_b16 v[134:135], v7 offset:0x2a00
	s_waitcnt lgkmcnt(6)
	v_mfma_f32_32x32x16_bf16 v[32:47], v[22:25], v[136:139], v[32:47]
	ds_read_b64_tr_b16 v[136:137], v7 offset:0x3200
	ds_read_b64_tr_b16 v[138:139], v7 offset:0x3a00
	s_waitcnt lgkmcnt(6)
	v_mfma_f32_32x32x16_bf16 v[48:63], v[8:11], v[26:29], v[48:63]
	ds_read_b64_tr_b16 v[26:27], v7 offset:0x400
	ds_read_b64_tr_b16 v[28:29], v7 offset:0xc00
	s_waitcnt lgkmcnt(6)
	v_mfma_f32_32x32x16_bf16 v[48:63], v[12:15], v[128:131], v[48:63]
	ds_read_b64_tr_b16 v[128:129], v7 offset:0x1400
	ds_read_b64_tr_b16 v[130:131], v7 offset:0x1c00
	s_waitcnt lgkmcnt(6)
	v_mfma_f32_32x32x16_bf16 v[48:63], v[18:21], v[132:135], v[48:63]
	ds_read_b64_tr_b16 v[132:133], v7 offset:0x2400
	ds_read_b64_tr_b16 v[134:135], v7 offset:0x2c00
	s_waitcnt lgkmcnt(6)
	v_mfma_f32_32x32x16_bf16 v[48:63], v[22:25], v[136:139], v[48:63]
	ds_read_b64_tr_b16 v[136:137], v7 offset:0x3400
	ds_read_b64_tr_b16 v[138:139], v7 offset:0x3c00
	s_waitcnt lgkmcnt(6)
	v_mfma_f32_32x32x16_bf16 v[64:79], v[8:11], v[26:29], v[64:79]
	ds_read_b64_tr_b16 v[26:27], v7 offset:0x600
	ds_read_b64_tr_b16 v[28:29], v7 offset:0xe00
	s_waitcnt lgkmcnt(6)
	v_mfma_f32_32x32x16_bf16 v[64:79], v[12:15], v[128:131], v[64:79]
	ds_read_b64_tr_b16 v[128:129], v7 offset:0x1600
	ds_read_b64_tr_b16 v[130:131], v7 offset:0x1e00
	s_waitcnt lgkmcnt(6)
	v_mfma_f32_32x32x16_bf16 v[64:79], v[18:21], v[132:135], v[64:79]
	ds_read_b64_tr_b16 v[132:133], v7 offset:0x2600
	ds_read_b64_tr_b16 v[134:135], v7 offset:0x2e00
	s_waitcnt lgkmcnt(6)
	v_mfma_f32_32x32x16_bf16 v[64:79], v[22:25], v[136:139], v[64:79]
	ds_read_b64_tr_b16 v[136:137], v7 offset:0x3600
	ds_read_b64_tr_b16 v[138:139], v7 offset:0x3e00
	s_waitcnt lgkmcnt(6)
	v_mfma_f32_32x32x16_bf16 v[80:95], v[8:11], v[26:29], v[80:95]
	v_max_f32_e32 v7, v113, v112
	v_max3_f32 v7, v7, v114, v115
	v_max3_f32 v7, v7, v116, v117
	v_max3_f32 v7, v7, v118, v119
	v_max3_f32 v7, v7, v120, v121
	v_max3_f32 v7, v7, v122, v123
	v_max3_f32 v7, v7, v124, v125
	v_max3_f32 v7, v7, v126, v127
	s_waitcnt lgkmcnt(4)
	v_mfma_f32_32x32x16_bf16 v[80:95], v[12:15], v[128:131], v[80:95]
	v_max3_f32 v7, v7, v96, v97
	v_max3_f32 v7, v7, v98, v99
	v_max3_f32 v7, v7, v100, v101
	v_max3_f32 v7, v7, v102, v103
	v_max3_f32 v7, v7, v104, v105
	v_max3_f32 v7, v7, v106, v107
	v_max3_f32 v7, v7, v108, v109
	v_max3_f32 v7, v7, v110, v111
	s_waitcnt lgkmcnt(2)
	v_mfma_f32_32x32x16_bf16 v[80:95], v[18:21], v[132:135], v[80:95]
	v_mov_b32_e32 v8, v7
	s_nop 1
	v_permlane32_swap_b32_e32 v7, v8
	v_max_f32_e32 v7, v8, v7
	v_sub_f32_e32 v8, v7, v2
	v_cmp_ge_f32_e32 vcc, 0x42b504f3, v8
	v_max_f32_e32 v8, v2, v7
	s_waitcnt lgkmcnt(0)
	v_mfma_f32_32x32x16_bf16 v[80:95], v[22:25], v[136:139], v[80:95]
	s_cmp_eq_u64 vcc, exec
	s_cbranch_scc0 .Lattn0_slowB
	v_mov_b32_e32 v7, 1.0
	v_mov_b32_e32 v214, v2

.LBB0_328:
	v_add_f32_e32 v2, 0, v230
	v_add_f32_e32 v2, v232, v2
	v_add_f32_e32 v2, v228, v2
	v_add_f32_e32 v2, v231, v2
	v_add_f32_e32 v2, v226, v2
	v_add_f32_e32 v2, v229, v2
	v_add_f32_e32 v2, v225, v2
	v_add_f32_e32 v2, v227, v2
	v_add_f32_e32 v2, v222, v2
	v_add_f32_e32 v2, v224, v2
	v_add_f32_e32 v2, v220, v2
	v_add_f32_e32 v2, v223, v2
	v_exp_f32_e32 v10, v128
	v_add_f32_e32 v2, v218, v2
	v_exp_f32_e32 v11, v129
	v_add_f32_e32 v2, v221, v2
	v_exp_f32_e32 v12, v130
	v_add_f32_e32 v2, v217, v2
	v_exp_f32_e32 v13, v131
	v_add_f32_e32 v2, v219, v2
	v_exp_f32_e32 v15, v132
	v_add_f32_e32 v2, v10, v2
	v_exp_f32_e32 v17, v133
	v_add_f32_e32 v2, v11, v2
	v_exp_f32_e32 v18, v134
	v_add_f32_e32 v2, v12, v2
	v_exp_f32_e32 v19, v135
	v_add_f32_e32 v2, v13, v2
	v_exp_f32_e32 v20, v136
	v_add_f32_e32 v2, v15, v2
	v_exp_f32_e32 v21, v137
	v_add_f32_e32 v2, v17, v2
	v_exp_f32_e32 v22, v138
	v_add_f32_e32 v2, v18, v2
	v_exp_f32_e32 v23, v139
	v_add_f32_e32 v2, v19, v2
	v_exp_f32_e32 v24, v140
	v_add_f32_e32 v2, v20, v2
	v_exp_f32_e32 v25, v141
	v_add_f32_e32 v2, v21, v2
	v_exp_f32_e32 v26, v142
	v_add_f32_e32 v2, v22, v2
	v_exp_f32_e32 v27, v143
	v_add_f32_e32 v2, v23, v2
	v_add_f32_e32 v2, v24, v2
	v_add_f32_e32 v2, v25, v2
	v_add_f32_e32 v2, v26, v2
	v_add_f32_e32 v215, v27, v2
	v_mov_b32_e32 v216, v215
	v_cvt_pk_bf16_f32 v2, v230, v232
	v_cvt_pk_bf16_f32 v3, v228, v231
	v_cvt_pk_bf16_f32 v4, v226, v229
	v_cvt_pk_bf16_f32 v5, v225, v227
	v_cvt_pk_bf16_f32 v6, v222, v224
	v_cvt_pk_bf16_f32 v7, v220, v223
	v_cvt_pk_bf16_f32 v8, v218, v221
	v_cvt_pk_bf16_f32 v9, v217, v219
	v_cvt_pk_bf16_f32 v10, v10, v11
	v_cvt_pk_bf16_f32 v11, v12, v13
	v_cvt_pk_bf16_f32 v12, v15, v17
	v_cvt_pk_bf16_f32 v13, v18, v19
	v_cvt_pk_bf16_f32 v18, v20, v21
	v_cvt_pk_bf16_f32 v19, v22, v23
	v_cvt_pk_bf16_f32 v20, v24, v25
	v_cvt_pk_bf16_f32 v21, v26, v27
	s_nop 1
	v_permlane32_swap_b32_e32 v215, v216
	s_cmp_gt_i32 s57, s6
	s_cbranch_scc1 .LBB0_330
	v_add_u32_e32 v15, s87, v206
	ds_read_b64_tr_b16 v[22:23], v15 offset:0
	ds_read_b64_tr_b16 v[24:25], v15 offset:0x800
	ds_read_b64_tr_b16 v[26:27], v15 offset:0x1000
	ds_read_b64_tr_b16 v[28:29], v15 offset:0x1800
	ds_read_b64_tr_b16 v[128:129], v15 offset:0x2000
	ds_read_b64_tr_b16 v[130:131], v15 offset:0x2800
	ds_read_b64_tr_b16 v[132:133], v15 offset:0x3000
	ds_read_b64_tr_b16 v[134:135], v15 offset:0x3800
	s_waitcnt lgkmcnt(0)
	s_nop 0
	v_mfma_f32_32x32x16_bf16 v[32:47], v[2:5], v[22:25], v[32:47]
	ds_read_b64_tr_b16 v[22:23], v15 offset:0x200
	ds_read_b64_tr_b16 v[24:25], v15 offset:0xa00
	v_mfma_f32_32x32x16_bf16 v[32:47], v[6:9], v[26:29], v[32:47]
	ds_read_b64_tr_b16 v[26:27], v15 offset:0x1200
	ds_read_b64_tr_b16 v[28:29], v15 offset:0x1a00
	v_mfma_f32_32x32x16_bf16 v[32:47], v[10:13], v[128:131], v[32:47]
	ds_read_b64_tr_b16 v[128:129], v15 offset:0x2200
	ds_read_b64_tr_b16 v[130:131], v15 offset:0x2a00
	v_mfma_f32_32x32x16_bf16 v[32:47], v[18:21], v[132:135], v[32:47]
	ds_read_b64_tr_b16 v[132:133], v15 offset:0x3200
	ds_read_b64_tr_b16 v[134:135], v15 offset:0x3a00
	s_waitcnt lgkmcnt(0)
	v_mfma_f32_32x32x16_bf16 v[48:63], v[2:5], v[22:25], v[48:63]
	ds_read_b64_tr_b16 v[22:23], v15 offset:0x400
	ds_read_b64_tr_b16 v[24:25], v15 offset:0xc00
	v_mfma_f32_32x32x16_bf16 v[48:63], v[6:9], v[26:29], v[48:63]
	ds_read_b64_tr_b16 v[26:27], v15 offset:0x1400
	ds_read_b64_tr_b16 v[28:29], v15 offset:0x1c00
	v_mfma_f32_32x32x16_bf16 v[48:63], v[10:13], v[128:131], v[48:63]
	ds_read_b64_tr_b16 v[128:129], v15 offset:0x2400
	ds_read_b64_tr_b16 v[130:131], v15 offset:0x2c00
	v_mfma_f32_32x32x16_bf16 v[48:63], v[18:21], v[132:135], v[48:63]
	ds_read_b64_tr_b16 v[132:133], v15 offset:0x3400
	ds_read_b64_tr_b16 v[134:135], v15 offset:0x3c00
	s_waitcnt lgkmcnt(0)
	v_mfma_f32_32x32x16_bf16 v[64:79], v[2:5], v[22:25], v[64:79]
	ds_read_b64_tr_b16 v[22:23], v15 offset:0x600
	ds_read_b64_tr_b16 v[24:25], v15 offset:0xe00
	v_mfma_f32_32x32x16_bf16 v[64:79], v[6:9], v[26:29], v[64:79]
	ds_read_b64_tr_b16 v[26:27], v15 offset:0x1600
	ds_read_b64_tr_b16 v[28:29], v15 offset:0x1e00
	v_mfma_f32_32x32x16_bf16 v[64:79], v[10:13], v[128:131], v[64:79]
	ds_read_b64_tr_b16 v[128:129], v15 offset:0x2600
	ds_read_b64_tr_b16 v[130:131], v15 offset:0x2e00
	v_mfma_f32_32x32x16_bf16 v[64:79], v[18:21], v[132:135], v[64:79]
	ds_read_b64_tr_b16 v[132:133], v15 offset:0x3600
	ds_read_b64_tr_b16 v[134:135], v15 offset:0x3e00
	s_waitcnt lgkmcnt(0)
	v_mfma_f32_32x32x16_bf16 v[80:95], v[2:5], v[22:25], v[80:95]
	v_mfma_f32_32x32x16_bf16 v[80:95], v[6:9], v[26:29], v[80:95]
	v_mfma_f32_32x32x16_bf16 v[80:95], v[10:13], v[128:131], v[80:95]
	v_mfma_f32_32x32x16_bf16 v[80:95], v[18:21], v[132:135], v[80:95]

.LBB0_347:
	v_cndmask_b32_e64 v23, v2, v214, s[4:5]
	v_mul_f32_e32 v2, 0xbe0293ee, v23
	v_fmamk_f32 v3, v112, 0x3e0293ee, v2
	v_fmamk_f32 v4, v113, 0x3e0293ee, v2
	v_exp_f32_e32 v3, v3
	v_fmamk_f32 v5, v114, 0x3e0293ee, v2
	v_exp_f32_e32 v4, v4
	v_fmamk_f32 v6, v115, 0x3e0293ee, v2
	v_exp_f32_e32 v5, v5
	v_fmamk_f32 v7, v116, 0x3e0293ee, v2
	v_fmamk_f32 v8, v117, 0x3e0293ee, v2
	v_fmamk_f32 v9, v118, 0x3e0293ee, v2
	v_fmamk_f32 v10, v119, 0x3e0293ee, v2
	v_fmamk_f32 v11, v120, 0x3e0293ee, v2
	v_fmamk_f32 v12, v121, 0x3e0293ee, v2
	v_fmamk_f32 v13, v122, 0x3e0293ee, v2
	v_fmamk_f32 v15, v123, 0x3e0293ee, v2
	v_fmamk_f32 v17, v124, 0x3e0293ee, v2
	v_fmamk_f32 v18, v125, 0x3e0293ee, v2
	v_fmamk_f32 v19, v126, 0x3e0293ee, v2
	v_fmamk_f32 v20, v127, 0x3e0293ee, v2
	v_fmamk_f32 v21, v96, 0x3e0293ee, v2
	v_fmamk_f32 v22, v97, 0x3e0293ee, v2
	v_fmamk_f32 v24, v98, 0x3e0293ee, v2
	v_fmamk_f32 v25, v99, 0x3e0293ee, v2
	v_fmamk_f32 v26, v100, 0x3e0293ee, v2
	v_fmamk_f32 v27, v101, 0x3e0293ee, v2
	v_fmamk_f32 v28, v102, 0x3e0293ee, v2
	v_fmamk_f32 v29, v103, 0x3e0293ee, v2
	v_fmamk_f32 v30, v104, 0x3e0293ee, v2
	v_fmamk_f32 v31, v105, 0x3e0293ee, v2
	v_fmamk_f32 v96, v106, 0x3e0293ee, v2
	v_fmamk_f32 v97, v107, 0x3e0293ee, v2
	v_fmamk_f32 v98, v108, 0x3e0293ee, v2
	v_fmamk_f32 v99, v109, 0x3e0293ee, v2
	v_fmamk_f32 v100, v110, 0x3e0293ee, v2
	v_fmac_f32_e32 v2, 0x3e0293ee, v111
	v_exp_f32_e32 v6, v6
	v_exp_f32_e32 v7, v7
	v_exp_f32_e32 v103, v2
	v_add_f32_e32 v2, 0, v3
	v_exp_f32_e32 v8, v8
	v_add_f32_e32 v2, v4, v2
	v_exp_f32_e32 v9, v9
	v_add_f32_e32 v2, v5, v2
	v_exp_f32_e32 v10, v10
	v_add_f32_e32 v2, v6, v2
	v_exp_f32_e32 v11, v11
	v_add_f32_e32 v2, v7, v2
	v_exp_f32_e32 v12, v12
	v_add_f32_e32 v2, v8, v2
	v_exp_f32_e32 v13, v13
	v_add_f32_e32 v2, v9, v2
	v_exp_f32_e32 v15, v15
	v_add_f32_e32 v2, v10, v2
	v_exp_f32_e32 v101, v17
	v_add_f32_e32 v2, v11, v2
	v_exp_f32_e32 v18, v18
	v_add_f32_e32 v2, v12, v2
	v_exp_f32_e32 v19, v19
	v_add_f32_e32 v2, v13, v2
	v_exp_f32_e32 v20, v20
	v_add_f32_e32 v2, v15, v2
	v_exp_f32_e32 v21, v21
	v_add_f32_e32 v2, v101, v2
	v_exp_f32_e32 v102, v22
	v_add_f32_e32 v2, v18, v2
	v_exp_f32_e32 v24, v24
	v_add_f32_e32 v2, v19, v2
	v_exp_f32_e32 v25, v25
	v_add_f32_e32 v2, v20, v2
	v_exp_f32_e32 v26, v26
	v_add_f32_e32 v2, v21, v2
	v_exp_f32_e32 v27, v27
	v_add_f32_e32 v2, v102, v2
	v_exp_f32_e32 v28, v28
	v_add_f32_e32 v2, v24, v2
	v_exp_f32_e32 v29, v29
	v_add_f32_e32 v2, v25, v2
	v_exp_f32_e32 v30, v30
	v_add_f32_e32 v2, v26, v2
	v_exp_f32_e32 v31, v31
	v_add_f32_e32 v2, v27, v2
	v_exp_f32_e32 v96, v96
	v_add_f32_e32 v2, v28, v2
	v_exp_f32_e32 v97, v97
	v_add_f32_e32 v2, v29, v2
	v_exp_f32_e32 v98, v98
	v_add_f32_e32 v2, v30, v2
	v_exp_f32_e32 v99, v99
	v_add_f32_e32 v2, v31, v2
	v_exp_f32_e32 v100, v100
	v_add_f32_e32 v2, v96, v2
	v_add_f32_e32 v2, v97, v2
	v_add_f32_e32 v2, v98, v2
	v_add_f32_e32 v2, v99, v2
	v_add_f32_e32 v2, v100, v2
	v_add_f32_e32 v17, v103, v2
	v_mov_b32_e32 v22, v17
	v_cvt_pk_bf16_f32 v2, v3, v4
	v_cvt_pk_bf16_f32 v3, v5, v6
	v_cvt_pk_bf16_f32 v4, v7, v8
	v_cvt_pk_bf16_f32 v5, v9, v10
	v_cvt_pk_bf16_f32 v6, v11, v12
	v_cvt_pk_bf16_f32 v7, v13, v15
	v_cvt_pk_bf16_f32 v8, v101, v18
	v_cvt_pk_bf16_f32 v9, v19, v20
	v_cvt_pk_bf16_f32 v10, v21, v102
	v_cvt_pk_bf16_f32 v11, v24, v25
	v_cvt_pk_bf16_f32 v12, v26, v27
	v_cvt_pk_bf16_f32 v13, v28, v29
	v_cvt_pk_bf16_f32 v18, v30, v31
	v_cvt_pk_bf16_f32 v19, v96, v97
	v_cvt_pk_bf16_f32 v20, v98, v99
	v_cvt_pk_bf16_f32 v21, v100, v103
	s_nop 1
	v_permlane32_swap_b32_e32 v17, v22
	s_andn2_b64 vcc, exec, s[70:71]
	s_cbranch_vccnz .LBB0_349
	v_add_u32_e32 v15, s83, v206
	ds_read_b64_tr_b16 v[24:25], v15 offset:0
	ds_read_b64_tr_b16 v[26:27], v15 offset:0x800
	ds_read_b64_tr_b16 v[28:29], v15 offset:0x1000
	ds_read_b64_tr_b16 v[30:31], v15 offset:0x1800
	ds_read_b64_tr_b16 v[96:97], v15 offset:0x2000
	ds_read_b64_tr_b16 v[98:99], v15 offset:0x2800
	ds_read_b64_tr_b16 v[100:101], v15 offset:0x3000
	ds_read_b64_tr_b16 v[102:103], v15 offset:0x3800
	s_waitcnt lgkmcnt(0)
	s_nop 0
	v_mfma_f32_32x32x16_bf16 v[32:47], v[2:5], v[24:27], v[32:47]
	ds_read_b64_tr_b16 v[24:25], v15 offset:0x200
	ds_read_b64_tr_b16 v[26:27], v15 offset:0xa00
	v_mfma_f32_32x32x16_bf16 v[32:47], v[6:9], v[28:31], v[32:47]
	ds_read_b64_tr_b16 v[28:29], v15 offset:0x1200
	ds_read_b64_tr_b16 v[30:31], v15 offset:0x1a00
	v_mfma_f32_32x32x16_bf16 v[32:47], v[10:13], v[96:99], v[32:47]
	ds_read_b64_tr_b16 v[96:97], v15 offset:0x2200
	ds_read_b64_tr_b16 v[98:99], v15 offset:0x2a00
	v_mfma_f32_32x32x16_bf16 v[32:47], v[18:21], v[100:103], v[32:47]
	ds_read_b64_tr_b16 v[100:101], v15 offset:0x3200
	ds_read_b64_tr_b16 v[102:103], v15 offset:0x3a00
	s_waitcnt lgkmcnt(0)
	v_mfma_f32_32x32x16_bf16 v[48:63], v[2:5], v[24:27], v[48:63]
	ds_read_b64_tr_b16 v[24:25], v15 offset:0x400
	ds_read_b64_tr_b16 v[26:27], v15 offset:0xc00
	v_mfma_f32_32x32x16_bf16 v[48:63], v[6:9], v[28:31], v[48:63]
	ds_read_b64_tr_b16 v[28:29], v15 offset:0x1400
	ds_read_b64_tr_b16 v[30:31], v15 offset:0x1c00
	v_mfma_f32_32x32x16_bf16 v[48:63], v[10:13], v[96:99], v[48:63]
	ds_read_b64_tr_b16 v[96:97], v15 offset:0x2400
	ds_read_b64_tr_b16 v[98:99], v15 offset:0x2c00
	v_mfma_f32_32x32x16_bf16 v[48:63], v[18:21], v[100:103], v[48:63]
	ds_read_b64_tr_b16 v[100:101], v15 offset:0x3400
	ds_read_b64_tr_b16 v[102:103], v15 offset:0x3c00
	s_waitcnt lgkmcnt(0)
	v_mfma_f32_32x32x16_bf16 v[64:79], v[2:5], v[24:27], v[64:79]
	ds_read_b64_tr_b16 v[24:25], v15 offset:0x600
	ds_read_b64_tr_b16 v[26:27], v15 offset:0xe00
	v_mfma_f32_32x32x16_bf16 v[64:79], v[6:9], v[28:31], v[64:79]
	ds_read_b64_tr_b16 v[28:29], v15 offset:0x1600
	ds_read_b64_tr_b16 v[30:31], v15 offset:0x1e00
	v_mfma_f32_32x32x16_bf16 v[64:79], v[10:13], v[96:99], v[64:79]
	ds_read_b64_tr_b16 v[96:97], v15 offset:0x2600
	ds_read_b64_tr_b16 v[98:99], v15 offset:0x2e00
	v_mfma_f32_32x32x16_bf16 v[64:79], v[18:21], v[100:103], v[64:79]
	ds_read_b64_tr_b16 v[100:101], v15 offset:0x3600
	ds_read_b64_tr_b16 v[102:103], v15 offset:0x3e00
	s_waitcnt lgkmcnt(0)
	v_mfma_f32_32x32x16_bf16 v[80:95], v[2:5], v[24:27], v[80:95]
	v_mfma_f32_32x32x16_bf16 v[80:95], v[6:9], v[28:31], v[80:95]
	v_mfma_f32_32x32x16_bf16 v[80:95], v[10:13], v[96:99], v[80:95]
	v_mfma_f32_32x32x16_bf16 v[80:95], v[18:21], v[100:103], v[80:95]

.LBB0_362:
	v_exp_f32_e32 v233, v128
	v_exp_f32_e32 v236, v129
	v_exp_f32_e32 v237, v130
	v_exp_f32_e32 v240, v131
	v_exp_f32_e32 v241, v132
	v_exp_f32_e32 v243, v133
	v_exp_f32_e32 v244, v134
	v_exp_f32_e32 v245, v135
	v_exp_f32_e32 v213, v136
	v_exp_f32_e32 v215, v137
	v_exp_f32_e32 v216, v138
	v_exp_f32_e32 v234, v139
	v_exp_f32_e32 v235, v140
	v_exp_f32_e32 v238, v141
	v_exp_f32_e32 v239, v142
	v_exp_f32_e32 v242, v143
	v_add_f32_e32 v1, 0, v230
	v_cndmask_b32_e64 v2, 0, 1, s[10:11]
	s_mov_b64 s[4:5], -1
	s_cmp_ge_i32 s56, s44
	v_add_f32_e32 v1, v232, v1
	v_cmp_ne_u32_e64 s[2:3], 1, v2
	s_cbranch_scc0 .LBB0_366
	v_add_f32_e32 v2, v228, v1
	v_add_f32_e32 v2, v231, v2
	v_add_f32_e32 v2, v226, v2
	v_add_f32_e32 v2, v229, v2
	v_add_f32_e32 v2, v225, v2
	v_add_f32_e32 v2, v227, v2
	v_add_f32_e32 v2, v222, v2
	v_add_f32_e32 v2, v224, v2
	v_add_f32_e32 v2, v220, v2
	v_add_f32_e32 v2, v223, v2
	v_add_f32_e32 v2, v218, v2
	v_add_f32_e32 v2, v221, v2
	v_add_f32_e32 v2, v217, v2
	v_add_f32_e32 v2, v219, v2
	v_add_f32_e32 v2, v233, v2
	v_add_f32_e32 v2, v236, v2
	v_add_f32_e32 v2, v237, v2
	v_add_f32_e32 v2, v240, v2
	v_add_f32_e32 v2, v241, v2
	v_add_f32_e32 v2, v243, v2
	v_add_f32_e32 v2, v244, v2
	v_add_f32_e32 v2, v245, v2
	v_add_f32_e32 v2, v213, v2
	v_add_f32_e32 v2, v215, v2
	v_add_f32_e32 v2, v216, v2
	v_add_f32_e32 v2, v234, v2
	v_add_f32_e32 v2, v235, v2
	v_add_f32_e32 v2, v238, v2
	v_add_f32_e32 v2, v239, v2
	v_add_f32_e32 v14, v242, v2
	v_mov_b32_e32 v17, v14
	v_cvt_pk_bf16_f32 v2, v230, v232
	v_cvt_pk_bf16_f32 v3, v228, v231
	v_cvt_pk_bf16_f32 v4, v226, v229
	v_cvt_pk_bf16_f32 v5, v225, v227
	v_cvt_pk_bf16_f32 v6, v222, v224
	v_cvt_pk_bf16_f32 v7, v220, v223
	v_cvt_pk_bf16_f32 v8, v218, v221
	v_cvt_pk_bf16_f32 v9, v217, v219
	v_cvt_pk_bf16_f32 v10, v233, v236
	v_cvt_pk_bf16_f32 v11, v237, v240
	v_cvt_pk_bf16_f32 v12, v241, v243
	v_cvt_pk_bf16_f32 v13, v244, v245
	v_cvt_pk_bf16_f32 v18, v213, v215
	v_cvt_pk_bf16_f32 v19, v216, v234
	v_cvt_pk_bf16_f32 v20, v235, v238
	v_cvt_pk_bf16_f32 v21, v239, v242
	s_nop 1
	v_permlane32_swap_b32_e32 v14, v17
	v_mov_b64_e32 v[158:159], v[94:95]
	v_mov_b64_e32 v[142:143], v[78:79]
	v_mov_b64_e32 v[126:127], v[62:63]
	v_mov_b64_e32 v[110:111], v[46:47]
	s_and_b64 vcc, exec, s[2:3]
	v_mov_b64_e32 v[156:157], v[92:93]
	v_mov_b64_e32 v[154:155], v[90:91]
	v_mov_b64_e32 v[152:153], v[88:89]
	v_mov_b64_e32 v[150:151], v[86:87]
	v_mov_b64_e32 v[148:149], v[84:85]
	v_mov_b64_e32 v[146:147], v[82:83]
	v_mov_b64_e32 v[144:145], v[80:81]
	v_mov_b64_e32 v[140:141], v[76:77]
	v_mov_b64_e32 v[138:139], v[74:75]
	v_mov_b64_e32 v[136:137], v[72:73]
	v_mov_b64_e32 v[134:135], v[70:71]
	v_mov_b64_e32 v[132:133], v[68:69]
	v_mov_b64_e32 v[130:131], v[66:67]
	v_mov_b64_e32 v[128:129], v[64:65]
	v_mov_b64_e32 v[124:125], v[60:61]
	v_mov_b64_e32 v[122:123], v[58:59]
	v_mov_b64_e32 v[120:121], v[56:57]
	v_mov_b64_e32 v[118:119], v[54:55]
	v_mov_b64_e32 v[116:117], v[52:53]
	v_mov_b64_e32 v[114:115], v[50:51]
	v_mov_b64_e32 v[112:113], v[48:49]
	v_mov_b64_e32 v[108:109], v[44:45]
	v_mov_b64_e32 v[106:107], v[42:43]
	v_mov_b64_e32 v[104:105], v[40:41]
	v_mov_b64_e32 v[102:103], v[38:39]
	v_mov_b64_e32 v[100:101], v[36:37]
	v_mov_b64_e32 v[98:99], v[34:35]
	v_mov_b64_e32 v[96:97], v[32:33]
	s_cbranch_vccnz .LBB0_365
	v_add_u32_e32 v30, s74, v206
	ds_read_b64_tr_b16 v[22:23], v30 offset:0
	ds_read_b64_tr_b16 v[24:25], v30 offset:0x800
	ds_read_b64_tr_b16 v[26:27], v30 offset:0x1000
	ds_read_b64_tr_b16 v[28:29], v30 offset:0x1800
	ds_read_b64_tr_b16 v[112:113], v30 offset:0x2000
	ds_read_b64_tr_b16 v[114:115], v30 offset:0x2800
	ds_read_b64_tr_b16 v[116:117], v30 offset:0x3000
	ds_read_b64_tr_b16 v[118:119], v30 offset:0x3800
	s_waitcnt lgkmcnt(0)
	s_nop 0
	v_mfma_f32_32x32x16_bf16 v[96:111], v[2:5], v[22:25], v[32:47]
	ds_read_b64_tr_b16 v[22:23], v30 offset:0x200
	ds_read_b64_tr_b16 v[24:25], v30 offset:0xa00
	v_mfma_f32_32x32x16_bf16 v[96:111], v[6:9], v[26:29], v[96:111]
	ds_read_b64_tr_b16 v[26:27], v30 offset:0x1200
	ds_read_b64_tr_b16 v[28:29], v30 offset:0x1a00
	ds_read_b64_tr_b16 v[128:129], v30 offset:0x2200
	ds_read_b64_tr_b16 v[130:131], v30 offset:0x2a00
	ds_read_b64_tr_b16 v[132:133], v30 offset:0x3200
	ds_read_b64_tr_b16 v[134:135], v30 offset:0x3a00
	s_waitcnt lgkmcnt(0)
	v_mfma_f32_32x32x16_bf16 v[96:111], v[10:13], v[112:115], v[96:111]
	v_mfma_f32_32x32x16_bf16 v[96:111], v[18:21], v[116:119], v[96:111]
	v_mfma_f32_32x32x16_bf16 v[112:127], v[2:5], v[22:25], v[48:63]
	ds_read_b64_tr_b16 v[22:23], v30 offset:0x400
	ds_read_b64_tr_b16 v[24:25], v30 offset:0xc00
	v_mfma_f32_32x32x16_bf16 v[112:127], v[6:9], v[26:29], v[112:127]
	ds_read_b64_tr_b16 v[26:27], v30 offset:0x1400
	ds_read_b64_tr_b16 v[28:29], v30 offset:0x1c00
	ds_read_b64_tr_b16 v[144:145], v30 offset:0x2400
	ds_read_b64_tr_b16 v[146:147], v30 offset:0x2c00
	ds_read_b64_tr_b16 v[148:149], v30 offset:0x3400
	ds_read_b64_tr_b16 v[150:151], v30 offset:0x3c00
	s_waitcnt lgkmcnt(0)
	v_mfma_f32_32x32x16_bf16 v[112:127], v[10:13], v[128:131], v[112:127]
	v_mfma_f32_32x32x16_bf16 v[112:127], v[18:21], v[132:135], v[112:127]
	v_mfma_f32_32x32x16_bf16 v[128:143], v[2:5], v[22:25], v[64:79]
	ds_read_b64_tr_b16 v[22:23], v30 offset:0x600
	ds_read_b64_tr_b16 v[24:25], v30 offset:0xe00
	v_mfma_f32_32x32x16_bf16 v[128:143], v[6:9], v[26:29], v[128:143]
	ds_read_b64_tr_b16 v[26:27], v30 offset:0x1600
	ds_read_b64_tr_b16 v[28:29], v30 offset:0x1e00
	ds_read_b64_tr_b16 v[246:247], v30 offset:0x2600
	ds_read_b64_tr_b16 v[248:249], v30 offset:0x2e00
	ds_read_b64_tr_b16 v[250:251], v30 offset:0x3600
	ds_read_b64_tr_b16 v[252:253], v30 offset:0x3e00
	s_waitcnt lgkmcnt(0)
	v_mfma_f32_32x32x16_bf16 v[128:143], v[10:13], v[144:147], v[128:143]
	v_mfma_f32_32x32x16_bf16 v[128:143], v[18:21], v[148:151], v[128:143]
	v_mfma_f32_32x32x16_bf16 v[144:159], v[2:5], v[22:25], v[80:95]
	v_mfma_f32_32x32x16_bf16 v[144:159], v[6:9], v[26:29], v[144:159]
	v_mfma_f32_32x32x16_bf16 v[144:159], v[10:13], v[246:249], v[144:159]
	v_mfma_f32_32x32x16_bf16 v[144:159], v[18:21], v[250:253], v[144:159]

.LBB0_371:
	v_add_f32_e32 v1, v228, v1
	v_add_f32_e32 v1, v231, v1
	v_add_f32_e32 v1, v226, v1
	v_add_f32_e32 v1, v229, v1
	v_add_f32_e32 v1, v225, v1
	v_add_f32_e32 v1, v227, v1
	v_add_f32_e32 v1, v222, v1
	v_add_f32_e32 v1, v224, v1
	v_add_f32_e32 v1, v220, v1
	v_add_f32_e32 v1, v223, v1
	v_add_f32_e32 v1, v218, v1
	v_add_f32_e32 v1, v221, v1
	v_add_f32_e32 v1, v217, v1
	v_add_f32_e32 v1, v219, v1
	v_add_f32_e32 v1, v233, v1
	v_add_f32_e32 v1, v236, v1
	v_add_f32_e32 v1, v237, v1
	v_add_f32_e32 v1, v240, v1
	v_add_f32_e32 v1, v241, v1
	v_add_f32_e32 v1, v243, v1
	v_add_f32_e32 v1, v244, v1
	v_add_f32_e32 v1, v245, v1
	v_add_f32_e32 v1, v213, v1
	v_add_f32_e32 v1, v215, v1
	v_add_f32_e32 v1, v216, v1
	v_add_f32_e32 v1, v234, v1
	v_add_f32_e32 v1, v235, v1
	v_add_f32_e32 v1, v238, v1
	v_add_f32_e32 v1, v239, v1
	v_add_f32_e32 v1, v242, v1
	v_mov_b32_e32 v14, v1
	v_cvt_pk_bf16_f32 v2, v230, v232
	v_cvt_pk_bf16_f32 v3, v228, v231
	v_cvt_pk_bf16_f32 v4, v226, v229
	v_cvt_pk_bf16_f32 v5, v225, v227
	v_cvt_pk_bf16_f32 v6, v222, v224
	v_cvt_pk_bf16_f32 v7, v220, v223
	v_cvt_pk_bf16_f32 v8, v218, v221
	v_cvt_pk_bf16_f32 v9, v217, v219
	v_cvt_pk_bf16_f32 v10, v233, v236
	v_cvt_pk_bf16_f32 v11, v237, v240
	v_cvt_pk_bf16_f32 v12, v241, v243
	v_cvt_pk_bf16_f32 v13, v244, v245
	v_cvt_pk_bf16_f32 v18, v213, v215
	v_cvt_pk_bf16_f32 v19, v216, v234
	v_cvt_pk_bf16_f32 v20, v235, v238
	v_cvt_pk_bf16_f32 v21, v239, v242
	s_nop 1
	v_permlane32_swap_b32_e32 v1, v14
	s_sub_i32 s44, s21, 64
	s_cmp_gt_i32 s44, s6
	s_cbranch_scc1 .LBB0_373
	v_add_u32_e32 v17, s74, v206
	ds_read_b64_tr_b16 v[22:23], v17 offset:0
	ds_read_b64_tr_b16 v[24:25], v17 offset:0x800
	ds_read_b64_tr_b16 v[26:27], v17 offset:0x1000
	ds_read_b64_tr_b16 v[28:29], v17 offset:0x1800
	ds_read_b64_tr_b16 v[128:129], v17 offset:0x2000
	ds_read_b64_tr_b16 v[130:131], v17 offset:0x2800
	ds_read_b64_tr_b16 v[132:133], v17 offset:0x3000
	ds_read_b64_tr_b16 v[134:135], v17 offset:0x3800
	s_waitcnt lgkmcnt(0)
	s_nop 0
	v_mfma_f32_32x32x16_bf16 v[32:47], v[2:5], v[22:25], v[32:47]
	ds_read_b64_tr_b16 v[22:23], v17 offset:0x200
	ds_read_b64_tr_b16 v[24:25], v17 offset:0xa00
	v_mfma_f32_32x32x16_bf16 v[32:47], v[6:9], v[26:29], v[32:47]
	ds_read_b64_tr_b16 v[26:27], v17 offset:0x1200
	ds_read_b64_tr_b16 v[28:29], v17 offset:0x1a00
	v_mfma_f32_32x32x16_bf16 v[32:47], v[10:13], v[128:131], v[32:47]
	ds_read_b64_tr_b16 v[128:129], v17 offset:0x2200
	ds_read_b64_tr_b16 v[130:131], v17 offset:0x2a00
	v_mfma_f32_32x32x16_bf16 v[32:47], v[18:21], v[132:135], v[32:47]
	ds_read_b64_tr_b16 v[132:133], v17 offset:0x3200
	ds_read_b64_tr_b16 v[134:135], v17 offset:0x3a00
	s_waitcnt lgkmcnt(0)
	v_mfma_f32_32x32x16_bf16 v[48:63], v[2:5], v[22:25], v[48:63]
	ds_read_b64_tr_b16 v[22:23], v17 offset:0x400
	ds_read_b64_tr_b16 v[24:25], v17 offset:0xc00
	v_mfma_f32_32x32x16_bf16 v[48:63], v[6:9], v[26:29], v[48:63]
	ds_read_b64_tr_b16 v[26:27], v17 offset:0x1400
	ds_read_b64_tr_b16 v[28:29], v17 offset:0x1c00
	v_mfma_f32_32x32x16_bf16 v[48:63], v[10:13], v[128:131], v[48:63]
	ds_read_b64_tr_b16 v[128:129], v17 offset:0x2400
	ds_read_b64_tr_b16 v[130:131], v17 offset:0x2c00
	v_mfma_f32_32x32x16_bf16 v[48:63], v[18:21], v[132:135], v[48:63]
	ds_read_b64_tr_b16 v[132:133], v17 offset:0x3400
	ds_read_b64_tr_b16 v[134:135], v17 offset:0x3c00
	s_waitcnt lgkmcnt(0)
	v_mfma_f32_32x32x16_bf16 v[64:79], v[2:5], v[22:25], v[64:79]
	ds_read_b64_tr_b16 v[22:23], v17 offset:0x600
	ds_read_b64_tr_b16 v[24:25], v17 offset:0xe00
	v_mfma_f32_32x32x16_bf16 v[64:79], v[6:9], v[26:29], v[64:79]
	ds_read_b64_tr_b16 v[26:27], v17 offset:0x1600
	ds_read_b64_tr_b16 v[28:29], v17 offset:0x1e00
	v_mfma_f32_32x32x16_bf16 v[64:79], v[10:13], v[128:131], v[64:79]
	ds_read_b64_tr_b16 v[128:129], v17 offset:0x2600
	ds_read_b64_tr_b16 v[130:131], v17 offset:0x2e00
	v_mfma_f32_32x32x16_bf16 v[64:79], v[18:21], v[132:135], v[64:79]
	ds_read_b64_tr_b16 v[132:133], v17 offset:0x3600
	ds_read_b64_tr_b16 v[134:135], v17 offset:0x3e00
	s_waitcnt lgkmcnt(0)
	v_mfma_f32_32x32x16_bf16 v[80:95], v[2:5], v[22:25], v[80:95]
	v_mfma_f32_32x32x16_bf16 v[80:95], v[6:9], v[26:29], v[80:95]
	v_mfma_f32_32x32x16_bf16 v[80:95], v[10:13], v[128:131], v[80:95]
	v_mfma_f32_32x32x16_bf16 v[80:95], v[18:21], v[132:135], v[80:95]

.LBB0_380:
	v_cndmask_b32_e64 v2, v2, v214, s[4:5]
	v_mul_f32_e32 v2, 0xbe0293ee, v2
	v_fmamk_f32 v3, v112, 0x3e0293ee, v2
	v_fmamk_f32 v4, v113, 0x3e0293ee, v2
	v_exp_f32_e32 v3, v3
	v_fmamk_f32 v5, v114, 0x3e0293ee, v2
	v_exp_f32_e32 v4, v4
	v_fmamk_f32 v6, v115, 0x3e0293ee, v2
	v_exp_f32_e32 v5, v5
	v_fmamk_f32 v7, v116, 0x3e0293ee, v2
	v_fmamk_f32 v8, v117, 0x3e0293ee, v2
	v_fmamk_f32 v9, v118, 0x3e0293ee, v2
	v_fmamk_f32 v10, v119, 0x3e0293ee, v2
	v_fmamk_f32 v11, v120, 0x3e0293ee, v2
	v_fmamk_f32 v12, v121, 0x3e0293ee, v2
	v_fmamk_f32 v13, v122, 0x3e0293ee, v2
	v_fmamk_f32 v18, v123, 0x3e0293ee, v2
	v_fmamk_f32 v19, v124, 0x3e0293ee, v2
	v_fmamk_f32 v20, v125, 0x3e0293ee, v2
	v_fmamk_f32 v21, v126, 0x3e0293ee, v2
	v_fmamk_f32 v22, v127, 0x3e0293ee, v2
	v_fmamk_f32 v23, v96, 0x3e0293ee, v2
	v_fmamk_f32 v24, v97, 0x3e0293ee, v2
	v_fmamk_f32 v25, v98, 0x3e0293ee, v2
	v_fmamk_f32 v26, v99, 0x3e0293ee, v2
	v_fmamk_f32 v27, v100, 0x3e0293ee, v2
	v_fmamk_f32 v28, v101, 0x3e0293ee, v2
	v_fmamk_f32 v29, v102, 0x3e0293ee, v2
	v_fmamk_f32 v30, v103, 0x3e0293ee, v2
	v_fmamk_f32 v31, v104, 0x3e0293ee, v2
	v_fmamk_f32 v96, v105, 0x3e0293ee, v2
	v_fmamk_f32 v97, v106, 0x3e0293ee, v2
	v_fmamk_f32 v98, v107, 0x3e0293ee, v2
	v_fmamk_f32 v99, v108, 0x3e0293ee, v2
	v_fmamk_f32 v100, v109, 0x3e0293ee, v2
	v_fmamk_f32 v101, v110, 0x3e0293ee, v2
	v_fmac_f32_e32 v2, 0x3e0293ee, v111
	v_exp_f32_e32 v6, v6
	v_exp_f32_e32 v7, v7
	v_exp_f32_e32 v104, v2
	v_add_f32_e32 v2, 0, v3
	v_exp_f32_e32 v8, v8
	v_add_f32_e32 v2, v4, v2
	v_exp_f32_e32 v9, v9
	v_add_f32_e32 v2, v5, v2
	v_exp_f32_e32 v10, v10
	v_add_f32_e32 v2, v6, v2
	v_exp_f32_e32 v11, v11
	v_add_f32_e32 v2, v7, v2
	v_exp_f32_e32 v12, v12
	v_add_f32_e32 v2, v8, v2
	v_exp_f32_e32 v13, v13
	v_add_f32_e32 v2, v9, v2
	v_exp_f32_e32 v18, v18
	v_add_f32_e32 v2, v10, v2
	v_exp_f32_e32 v19, v19
	v_add_f32_e32 v2, v11, v2
	v_exp_f32_e32 v20, v20
	v_add_f32_e32 v2, v12, v2
	v_exp_f32_e32 v21, v21
	v_add_f32_e32 v2, v13, v2
	v_exp_f32_e32 v102, v22
	v_add_f32_e32 v2, v18, v2
	v_exp_f32_e32 v103, v23
	v_add_f32_e32 v2, v19, v2
	v_exp_f32_e32 v24, v24
	v_add_f32_e32 v2, v20, v2
	v_exp_f32_e32 v25, v25
	v_add_f32_e32 v2, v21, v2
	v_exp_f32_e32 v26, v26
	v_add_f32_e32 v2, v102, v2
	v_exp_f32_e32 v27, v27
	v_add_f32_e32 v2, v103, v2
	v_exp_f32_e32 v28, v28
	v_add_f32_e32 v2, v24, v2
	v_exp_f32_e32 v29, v29
	v_add_f32_e32 v2, v25, v2
	v_exp_f32_e32 v30, v30
	v_add_f32_e32 v2, v26, v2
	v_exp_f32_e32 v31, v31
	v_add_f32_e32 v2, v27, v2
	v_exp_f32_e32 v96, v96
	v_add_f32_e32 v2, v28, v2
	v_exp_f32_e32 v97, v97
	v_add_f32_e32 v2, v29, v2
	v_exp_f32_e32 v98, v98
	v_add_f32_e32 v2, v30, v2
	v_exp_f32_e32 v99, v99
	v_add_f32_e32 v2, v31, v2
	v_exp_f32_e32 v100, v100
	v_add_f32_e32 v2, v96, v2
	v_exp_f32_e32 v101, v101
	v_add_f32_e32 v2, v97, v2
	v_add_f32_e32 v2, v98, v2
	v_add_f32_e32 v2, v99, v2
	v_add_f32_e32 v2, v100, v2
	v_add_f32_e32 v2, v101, v2
	s_waitcnt vmcnt(0) lgkmcnt(0)
	s_barrier
	v_add_f32_e32 v22, v104, v2
	v_mov_b32_e32 v23, v22
	v_cvt_pk_bf16_f32 v2, v3, v4
	v_cvt_pk_bf16_f32 v3, v5, v6
	v_cvt_pk_bf16_f32 v4, v7, v8
	v_cvt_pk_bf16_f32 v5, v9, v10
	v_cvt_pk_bf16_f32 v6, v11, v12
	v_cvt_pk_bf16_f32 v7, v13, v18
	v_cvt_pk_bf16_f32 v8, v19, v20
	v_cvt_pk_bf16_f32 v9, v21, v102
	v_cvt_pk_bf16_f32 v10, v103, v24
	v_cvt_pk_bf16_f32 v11, v25, v26
	v_cvt_pk_bf16_f32 v12, v27, v28
	v_cvt_pk_bf16_f32 v13, v29, v30
	v_cvt_pk_bf16_f32 v18, v31, v96
	v_cvt_pk_bf16_f32 v19, v97, v98
	v_cvt_pk_bf16_f32 v20, v99, v100
	v_cvt_pk_bf16_f32 v21, v101, v104
	s_nop 1
	v_permlane32_swap_b32_e32 v22, v23
	s_and_b64 vcc, exec, s[2:3]
	s_cbranch_vccnz .LBB0_382
	v_add_u32_e32 v104, s87, v206
	ds_read_b64_tr_b16 v[24:25], v104 offset:0
	ds_read_b64_tr_b16 v[26:27], v104 offset:0x800
	ds_read_b64_tr_b16 v[28:29], v104 offset:0x1000
	ds_read_b64_tr_b16 v[30:31], v104 offset:0x1800
	ds_read_b64_tr_b16 v[96:97], v104 offset:0x2000
	ds_read_b64_tr_b16 v[98:99], v104 offset:0x2800
	ds_read_b64_tr_b16 v[100:101], v104 offset:0x3000
	ds_read_b64_tr_b16 v[102:103], v104 offset:0x3800
	s_waitcnt lgkmcnt(0)
	s_nop 0
	v_mfma_f32_32x32x16_bf16 v[32:47], v[2:5], v[24:27], v[32:47]
	ds_read_b64_tr_b16 v[24:25], v104 offset:0x200
	ds_read_b64_tr_b16 v[26:27], v104 offset:0xa00
	v_mfma_f32_32x32x16_bf16 v[32:47], v[6:9], v[28:31], v[32:47]
	ds_read_b64_tr_b16 v[28:29], v104 offset:0x1200
	ds_read_b64_tr_b16 v[30:31], v104 offset:0x1a00
	v_mfma_f32_32x32x16_bf16 v[32:47], v[10:13], v[96:99], v[32:47]
	ds_read_b64_tr_b16 v[96:97], v104 offset:0x2200
	ds_read_b64_tr_b16 v[98:99], v104 offset:0x2a00
	v_mfma_f32_32x32x16_bf16 v[32:47], v[18:21], v[100:103], v[32:47]
	ds_read_b64_tr_b16 v[100:101], v104 offset:0x3200
	ds_read_b64_tr_b16 v[102:103], v104 offset:0x3a00
	s_waitcnt lgkmcnt(0)
	v_mfma_f32_32x32x16_bf16 v[48:63], v[2:5], v[24:27], v[48:63]
	ds_read_b64_tr_b16 v[24:25], v104 offset:0x400
	ds_read_b64_tr_b16 v[26:27], v104 offset:0xc00
	v_mfma_f32_32x32x16_bf16 v[48:63], v[6:9], v[28:31], v[48:63]
	ds_read_b64_tr_b16 v[28:29], v104 offset:0x1400
	ds_read_b64_tr_b16 v[30:31], v104 offset:0x1c00
	v_mfma_f32_32x32x16_bf16 v[48:63], v[10:13], v[96:99], v[48:63]
	ds_read_b64_tr_b16 v[96:97], v104 offset:0x2400
	ds_read_b64_tr_b16 v[98:99], v104 offset:0x2c00
	v_mfma_f32_32x32x16_bf16 v[48:63], v[18:21], v[100:103], v[48:63]
	ds_read_b64_tr_b16 v[100:101], v104 offset:0x3400
	ds_read_b64_tr_b16 v[102:103], v104 offset:0x3c00
	s_waitcnt lgkmcnt(0)
	v_mfma_f32_32x32x16_bf16 v[64:79], v[2:5], v[24:27], v[64:79]
	ds_read_b64_tr_b16 v[24:25], v104 offset:0x600
	ds_read_b64_tr_b16 v[26:27], v104 offset:0xe00
	v_mfma_f32_32x32x16_bf16 v[64:79], v[6:9], v[28:31], v[64:79]
	ds_read_b64_tr_b16 v[28:29], v104 offset:0x1600
	ds_read_b64_tr_b16 v[30:31], v104 offset:0x1e00
	v_mfma_f32_32x32x16_bf16 v[64:79], v[10:13], v[96:99], v[64:79]
	ds_read_b64_tr_b16 v[96:97], v104 offset:0x2600
	ds_read_b64_tr_b16 v[98:99], v104 offset:0x2e00
	v_mfma_f32_32x32x16_bf16 v[64:79], v[18:21], v[100:103], v[64:79]
	ds_read_b64_tr_b16 v[100:101], v104 offset:0x3600
	ds_read_b64_tr_b16 v[102:103], v104 offset:0x3e00
	s_waitcnt lgkmcnt(0)
	v_mfma_f32_32x32x16_bf16 v[80:95], v[2:5], v[24:27], v[80:95]
	v_mfma_f32_32x32x16_bf16 v[80:95], v[6:9], v[28:31], v[80:95]
	v_mfma_f32_32x32x16_bf16 v[80:95], v[10:13], v[96:99], v[80:95]
	v_mfma_f32_32x32x16_bf16 v[80:95], v[18:21], v[100:103], v[80:95]
